# planA + planW: fifth-round mixer chunks pre-processed by idle WGs during W_in last partial round (group counters)
# speedup vs baseline: 1.0055x; 1.0029x over previous
; __device__ __forceinline__ unsigned xb_ld(unsigned* p)              { return __hip_atomic_load(p, __ATOMIC_RELAXED, __HIP_MEMORY_SCOPE_AGENT); }
;     __device__ __forceinline__ bool next(int i, Unit& u) const {
;         const long L = (long)i * G + c; if (L >= nwg) return false;
;         const int xcd = (int)(L % NXCD), off = (int)(L / NXCD), own = 8 * nN, grp = WGM * nN;
;         u.kb = 0;
;         if (off < own) { const int g2 = off / grp, idg = off - g2 * grp; u.pm = 8 * xcd + WGM * g2 + (idg % WGM); u.pn = (idg / WGM + xcd * ((nN + NXCD - 1) / NXCD)) % nN; }
;         else { const int q = nwg / NXCD, r = nwg % NXCD, id = xcd * (q - own) + (xcd < r ? xcd : r) + (off - own); u.pm = 64 + (id & 1); u.pn = id >> 1; }
; __device__ __forceinline__ void xcd_barrier_complete(unsigned* bar, unsigned x, unsigned& nloc, unsigned& nx) {
;     const unsigned G = gridDim.x * gridDim.y * gridDim.z;
;     unsigned sum, cnt, mine, sp = 0u;
;     for (;;) {
;         sum = 0u; cnt = 0u; mine = 0u;
; #pragma unroll
;         for (unsigned j = 0; j < 16; ++j) { const unsigned c = xb_ld(&bar[XB_XCNT(j)]); sum += c; cnt += (c > 0u) ? 1u : 0u; mine = (j == x) ? c : mine; }
;         if (sum == G) break;
;         __builtin_amdgcn_s_sleep(1);
;         if ((++sp & 255u) == 0u) { if (xb_ld(&bar[XB_TMO])) break; if (sp > XB_SPIN_CAP) { atomicAdd(&bar[XB_TMO], 1u); break; } }
;     }
;     nloc = mine > 0u ? mine : 1u; nx = cnt > 0u ? cnt : 1u;
; }
.LBB0_117:
	v_writelane_b32 v247, s48, 37
	s_nop 1
	v_writelane_b32 v247, s49, 38
	v_writelane_b32 v247, s50, 39
	v_writelane_b32 v247, s51, 40
	v_writelane_b32 v247, s52, 41
	v_writelane_b32 v247, s53, 42
	v_writelane_b32 v247, s54, 43
	v_writelane_b32 v247, s55, 44
	v_writelane_b32 v247, s56, 45
	v_writelane_b32 v247, s57, 46
	v_writelane_b32 v247, s58, 47
	v_writelane_b32 v247, s59, 48
	v_writelane_b32 v247, s60, 49
	v_writelane_b32 v247, s61, 50
	v_writelane_b32 v247, s62, 51
	v_writelane_b32 v247, s63, 52
	s_or_b64 exec, exec, s[0:1]
	s_add_u32 s6, s98, 0x17d00000
	s_addc_u32 s7, s99, 0
	s_add_u32 s14, s98, 0x23300000
	s_addc_u32 s15, s99, 0
	s_cmpk_lt_i32 s65, 0xb58
	s_cselect_b64 s[0:1], -1, 0
	v_writelane_b32 v247, s0, 53
	s_ashr_i32 s69, s65, 31
	s_ashr_i32 s68, s20, 31
	v_writelane_b32 v247, s1, 54
	s_lshr_b32 s0, s69, 29
	s_add_i32 s0, s65, s0
	s_ashr_i32 s11, s0, 3
	s_and_b32 s0, s0, -8
	s_sub_i32 s10, s65, s0
	s_mul_i32 s0, s10, 11
	s_add_i32 s0, s11, s0
	s_addk_i32 s0, 0xfea0
	s_and_b32 s1, s0, 1
	s_ashr_i32 s5, s0, 1
	s_mul_hi_i32 s0, s65, 0x2e8ba2e9
	s_or_b32 s4, s1, 64
	s_lshr_b32 s1, s0, 31
	s_ashr_i32 s0, s0, 8
	s_add_i32 s0, s0, s1
	s_mul_i32 s1, s0, 0xffffff50
	s_add_i32 s1, s1, s11
	s_lshl_b32 s12, s10, 3
	s_lshl_b32 s0, s0, 2
	s_add_i32 s8, s0, s12
	s_ashr_i32 s0, s1, 31
	s_lshr_b32 s0, s0, 30
	s_add_i32 s0, s1, s0
	s_ashr_i32 s9, s0, 2
	s_and_b32 s0, s0, -4
	s_sub_i32 s0, s1, s0
	s_add_i32 s8, s8, s0
	s_mul_i32 s0, s10, 6
	s_add_i32 s9, s9, s0
	s_mul_hi_i32 s0, s9, 0x2e8ba2e9
	s_lshr_b32 s1, s0, 31
	s_ashr_i32 s0, s0, 3
	s_add_i32 s0, s0, s1
	s_mul_i32 s0, s0, 44
	s_sub_i32 s9, s9, s0
	s_add_u32 s0, s98, 0x80200
	s_addc_u32 s1, s99, 0
	s_add_u32 s92, s98, 0x80400
	s_addc_u32 s93, s99, 0
	s_add_u32 s74, s98, 0x80500
	s_addc_u32 s75, s99, 0
	s_add_u32 s80, s98, 0x80600
	s_addc_u32 s81, s99, 0
	s_add_u32 s82, s98, 0x80700
	v_writelane_b32 v247, s0, 55
	s_addc_u32 s83, s99, 0
	v_lshl_add_u64 v[0:1], v[0:1], 2, s[24:25]
	v_writelane_b32 v247, s1, 56
	s_add_u32 s0, s98, 0x80800
	s_addc_u32 s1, s99, 0
	v_writelane_b32 v247, s0, 57
	v_mov_b32_e32 v189, 0
	v_mov_b32_e32 v218, 0x358637bd
	v_writelane_b32 v247, s1, 58
	s_add_u32 s0, s98, 0x80900
	s_addc_u32 s1, s99, 0
	v_writelane_b32 v247, s0, 59
	v_mov_b32_e32 v219, 1
	v_mov_b64_e32 v[190:191], 0xb58
	v_writelane_b32 v247, s1, 60
	s_add_u32 s0, s98, 0x80a00
	s_addc_u32 s1, s99, 0
	v_writelane_b32 v247, s0, 61
	v_mov_b64_e32 v[192:193], 0xb57
	v_mov_b64_e32 v[194:195], 0x200
	v_writelane_b32 v247, s1, 62
	s_add_u32 s0, s98, 0x80b00
	s_addc_u32 s1, s99, 0
	v_writelane_b32 v247, s0, 63
	v_mov_b64_e32 v[196:197], 0x1ff
	v_mbcnt_hi_u32_b32 v217, -1, v6
	v_writelane_b32 v245, s1, 0
	s_add_u32 s0, s98, 0x80c00
	s_addc_u32 s1, s99, 0
	v_writelane_b32 v245, s0, 1
	v_mov_b64_e32 v[198:199], 0x462
	v_mov_b64_e32 v[200:201], 0x461
	v_writelane_b32 v245, s1, 2
	s_add_u32 s0, s98, 0x80d00
	s_addc_u32 s1, s99, 0
	v_writelane_b32 v245, s0, 3
	v_mov_b32_e32 v220, 0x7800
	s_movk_i32 s33, 0xc00
	v_writelane_b32 v245, s1, 4
	s_add_u32 s0, s98, 0x80e00
	s_addc_u32 s1, s99, 0
	v_writelane_b32 v245, s0, 5
	s_mov_b32 s85, 0
	s_mov_b64 s[86:87], 0x80
	v_writelane_b32 v245, s1, 6
	s_add_u32 s0, s98, 0x80f00
	s_addc_u32 s1, s99, 0
	v_writelane_b32 v245, s0, 7
	s_barrier
	s_nop 0
	v_writelane_b32 v245, s1, 8
	s_add_u32 s0, s98, 0x81000
	s_addc_u32 s1, s99, 0
	v_writelane_b32 v245, s0, 9
	s_nop 1
	v_writelane_b32 v245, s1, 10
	s_add_u32 s0, s98, 0x81100
	s_addc_u32 s1, s99, 0
	v_writelane_b32 v245, s0, 11
	s_nop 1
	v_writelane_b32 v245, s1, 12
	s_add_u32 s0, s98, 0x81200
	s_addc_u32 s1, s99, 0
	v_writelane_b32 v245, s0, 13
	s_nop 1
	v_writelane_b32 v245, s1, 14
	s_add_u32 s0, s98, 0x81300
	s_addc_u32 s1, s99, 0
	v_writelane_b32 v245, s0, 15
	s_cmp_eq_u32 s3, 15
	s_nop 0
	v_writelane_b32 v245, s1, 16
	s_cselect_b64 s[0:1], -1, 0
	v_writelane_b32 v245, s0, 17
	s_cmp_eq_u32 s3, 14
	s_nop 0
	v_writelane_b32 v245, s1, 18
	s_cselect_b64 s[0:1], -1, 0
	v_writelane_b32 v245, s0, 19
	s_cmp_eq_u32 s3, 13
	s_nop 0
	v_writelane_b32 v245, s1, 20
	s_cselect_b64 s[0:1], -1, 0
	v_writelane_b32 v245, s0, 21
	s_cmp_eq_u32 s3, 12
	s_nop 0
	v_writelane_b32 v245, s1, 22
	s_cselect_b64 s[0:1], -1, 0
	v_writelane_b32 v245, s0, 23
	s_cmp_eq_u32 s3, 11
	s_nop 0
	v_writelane_b32 v245, s1, 24
	s_cselect_b64 s[0:1], -1, 0
	v_writelane_b32 v245, s0, 25
	s_cmp_eq_u32 s3, 10
	s_nop 0
	v_writelane_b32 v245, s1, 26
	s_cselect_b64 s[0:1], -1, 0
	v_writelane_b32 v245, s0, 27
	s_cmp_eq_u32 s3, 9
	s_nop 0
	v_writelane_b32 v245, s1, 28
	s_cselect_b64 s[0:1], -1, 0
	v_writelane_b32 v245, s0, 29
	s_cmp_eq_u32 s3, 8
	s_nop 0
	v_writelane_b32 v245, s1, 30
	s_cselect_b64 s[0:1], -1, 0
	v_writelane_b32 v245, s0, 31
	s_cmp_eq_u32 s3, 7
	s_nop 0
	v_writelane_b32 v245, s1, 32
	s_cselect_b64 s[0:1], -1, 0
	v_writelane_b32 v245, s0, 33
	s_cmp_eq_u32 s3, 6
	s_nop 0
	v_writelane_b32 v245, s1, 34
	s_cselect_b64 s[0:1], -1, 0
	v_writelane_b32 v245, s0, 35
	s_cmp_eq_u32 s3, 5
	s_nop 0
	v_writelane_b32 v245, s1, 36
	s_cselect_b64 s[0:1], -1, 0
	v_writelane_b32 v245, s0, 37
	s_cmp_eq_u32 s3, 4
	s_nop 0
	v_writelane_b32 v245, s1, 38
	s_cselect_b64 s[0:1], -1, 0
	v_writelane_b32 v245, s0, 39
	s_cmp_eq_u32 s3, 3
	s_nop 0
	v_writelane_b32 v245, s1, 40
	s_cselect_b64 s[0:1], -1, 0
	v_writelane_b32 v245, s0, 41
	s_cmp_eq_u32 s3, 2
	s_nop 0
	v_writelane_b32 v245, s1, 42
	s_cselect_b64 s[0:1], -1, 0
	v_writelane_b32 v245, s0, 43
	s_cmp_eq_u32 s3, 1
	s_nop 0
	v_writelane_b32 v245, s1, 44
	s_cselect_b64 s[0:1], -1, 0
	v_writelane_b32 v245, s0, 45
	s_cmp_eq_u32 s3, 0
	s_nop 0
	v_writelane_b32 v245, s1, 46
	s_cselect_b64 s[0:1], -1, 0
	v_writelane_b32 v245, s0, 47
;     __device__ __forceinline__ bool next(int i, Unit& u) const {
;         if (i != 0 || c >= 64) return false;
;         u.pm = 64 + (c & 1); u.pn = (c >> 1) & 7; u.kb = (c >> 4) * kslice; return true;
;     }
;     __device__ __forceinline__ void operator()(const f32x4 (&acc)[2][2][4][2], const Unit& u, int wr, int wc, int fr, int fq, const float (&)[8]) const {
;         const int row0 = (u.pm - 64) * BM + wr * 64 + fr, col0 = u.pn * BM + wc * 32 + 8 * fq;
;         float* sp = slab + (size_t)(u.kb / kslice) * (MS * DM);
; __device__ __forceinline__ void mixer_mid(const Params& p, LAS unsigned char* lds, int G, int layer) {
;     ...
;     const int mx_x = (G % 8 == 0) ? (int)(blockIdx.x & 7) : 0, mx_r = (G % 8 == 0) ? (int)(blockIdx.x >> 3) : (int)blockIdx.x, mx_n = (G % 8 == 0) ? G / 8 : G, mx_tot = (G % 8 == 0) ? NCH_X : NCH;
;     u32x4 ra[5], rg[5]; bool preloaded = false;
;     ...
;     for (int ci = mx_r; ci < mx_tot; ci += mx_n) {
	s_nop 1
	v_writelane_b32 v245, s1, 48
	s_add_u32 s0, s98, 0x83400
	s_addc_u32 s1, s99, 0
	v_writelane_b32 v245, s0, 49
	s_nop 1
	v_writelane_b32 v245, s1, 50
	s_add_u32 s0, s98, 0x83500
	s_addc_u32 s1, s99, 0
	v_writelane_b32 v245, s0, 51
	s_nop 1
	v_writelane_b32 v245, s1, 52
	s_add_u32 s0, s98, 0x28500000
	s_addc_u32 s1, s99, 0
	v_writelane_b32 v245, s0, 53
	s_cmpk_lt_i32 s65, 0x200
	s_nop 0
	v_writelane_b32 v245, s1, 54
	s_cselect_b64 s[0:1], -1, 0
	v_writelane_b32 v245, s0, 55
	s_nop 1
	v_writelane_b32 v245, s1, 56
	s_lshr_b32 s0, s69, 24
	s_add_i32 s0, s65, s0
	s_ashr_i32 s0, s0, 8
	s_lshl_b32 s1, s0, 5
	s_sub_i32 s1, s11, s1
	s_lshr_b32 s3, s1, 30
	s_add_i32 s3, s1, s3
	s_and_b32 s13, s3, -4
	s_lshl_b32 s0, s0, 2
	s_sub_i32 s1, s1, s13
	s_add_i32 s0, s0, s12
	s_ashr_i32 s3, s3, 2
	s_add_i32 s26, s0, s1
	s_add_i32 s0, s3, s10
	s_ashr_i32 s1, s0, 31
	s_lshr_b32 s1, s1, 29
	s_add_i32 s1, s0, s1
	s_and_b32 s1, s1, -8
	s_sub_i32 s28, s0, s1
	s_add_u32 s18, s98, 0x27500000
	s_addc_u32 s19, s99, 0
	s_sub_u32 s100, s65, 88
	s_cmp_lt_u32 s100, 64
	s_cselect_b64 s[0:1], -1, 0
	v_writelane_b32 v245, s0, 57
	s_and_b32 s13, s100, 1
	s_or_b32 s22, s13, 64
	v_writelane_b32 v245, s1, 58
	s_ashr_i32 s0, s100, 4
	s_mul_i32 s30, s0, 0xb00
	s_bfe_u32 s3, s100, 0x30001
	s_mul_i32 s1, s22, 0x2c0000
	s_ashr_i32 s31, s30, 31
	s_add_u32 s1, s6, s1
	s_addc_u32 s16, s7, 0
	s_add_u32 s34, s1, s30
	s_addc_u32 s35, s16, s31
	s_add_u32 s16, s34, 0x160000
	v_writelane_b32 v245, s34, 59
	s_addc_u32 s17, s35, 0
	s_ashr_i32 s1, s0, 31
	v_writelane_b32 v245, s35, 60
	v_writelane_b32 v245, s16, 61
	s_lshl_b32 s23, s22, 8
	s_lshl_b32 s2, s3, 8
	v_writelane_b32 v245, s17, 62
	s_lshl_b64 s[16:17], s[0:1], 22
	s_add_u32 s16, s18, s16
	v_writelane_b32 v244, s18, 0
	s_addc_u32 s17, s19, s17
	s_add_i32 s1, s23, 0xffffc000
	v_writelane_b32 v244, s19, 1
	v_writelane_b32 v244, s16, 2
	s_cmpk_lt_i32 s65, 0x462
	v_writelane_b32 v245, s2, 63
	v_writelane_b32 v244, s17, 3
	s_mov_b64 s[16:17], 0x1400
	v_lshl_add_u64 v[184:185], v[0:1], 0, s[16:17]
	s_mov_b64 s[16:17], 0x2400
	v_lshl_add_u64 v[186:187], v[0:1], 0, s[16:17]
	v_writelane_b32 v244, s1, 4
	s_cselect_b64 s[16:17], -1, 0
	s_mul_hi_i32 s1, s65, 0x78787879
	v_writelane_b32 v244, s16, 5
	s_lshr_b32 s23, s65, 3
	s_ashr_i32 s24, s20, 3
	v_writelane_b32 v244, s17, 6
	s_lshr_b32 s16, s1, 31
	s_ashr_i32 s1, s1, 8
	s_add_i32 s1, s1, s16
	s_min_i32 s16, s10, 2
	s_mul_i32 s17, s1, 0xffffffbc
	s_add_i32 s16, s16, s11
	s_add_i32 s11, s17, s11
	s_lshl_b32 s1, s1, 2
	s_add_i32 s1, s1, s12
	s_ashr_i32 s12, s11, 31
	s_lshr_b32 s12, s12, 30
	s_add_i32 s12, s11, s12
	s_and_b32 s17, s12, -4
	s_sub_i32 s11, s11, s17
	s_add_i32 s11, s1, s11
	s_ashr_i32 s1, s12, 2
	s_mul_i32 s12, s10, 3
	s_add_i32 s1, s1, s12
	s_mul_hi_i32 s12, s1, 0x78787879
	s_lshr_b32 s17, s12, 31
	s_ashr_i32 s12, s12, 3
	s_add_i32 s12, s12, s17
	s_mul_i32 s12, s12, 17
	s_sub_i32 s12, s1, s12
	s_lshl_b32 s1, s10, 2
	s_add_i32 s1, s1, s16
	s_addk_i32 s1, 0xff78
	s_and_b32 s10, s16, 1
	s_or_b32 s10, s10, 64
	s_ashr_i32 s16, s1, 1
	s_and_b32 s1, s20, 7
	s_and_b32 s17, s65, 7
	s_cmp_eq_u32 s1, 0
	s_mulk_i32 s17, 0x84
	s_cselect_b32 s1, s17, 0
	v_writelane_b32 v244, s1, 7
	s_movk_i32 s1, 0x420
	s_cselect_b32 s17, s24, s20
	s_cselect_b32 s2, s23, s65
	s_cselect_b32 s1, 0x84, s1
	v_writelane_b32 v244, s17, 8
	s_add_i32 s2, s2, 4
	v_writelane_b32 v244, s2, 9
	s_cmp_lt_i32 s2, s1
	v_writelane_b32 v244, s1, 10
	s_cselect_b64 s[18:19], -1, 0
	v_writelane_b32 v244, s18, 11
	s_lshl_b32 s17, s0, 10
	s_lshl_b32 s0, s22, 20
	v_writelane_b32 v244, s19, 12
	s_ashr_i32 s18, s17, 31
	s_lshl_b32 s1, s3, 20
	s_add_u32 s0, s14, s0
	v_writelane_b32 v244, s1, 13
	s_addc_u32 s1, s15, 0
	s_add_u32 s0, s0, s17
	s_addc_u32 s1, s1, s18
	s_add_u32 s22, s0, 0x80000
	v_writelane_b32 v244, s0, 14
	s_addc_u32 s23, s1, 0
	s_cmpk_lt_i32 s65, 0xb00
	v_writelane_b32 v244, s1, 15
	v_writelane_b32 v244, s22, 16
	s_cselect_b32 s4, s8, s4
	s_mul_i32 s2, s28, 0x2c0000
	v_writelane_b32 v244, s23, 17
	s_cselect_b32 s22, s9, s5
	s_ashr_i32 s5, s4, 31
	s_lshl_b64 s[0:1], s[4:5], 20
	s_add_u32 s8, s72, s0
	s_mov_b32 s0, s22
	s_addc_u32 s9, s73, s1
	s_ashr_i32 s23, s22, 31
	v_writelane_b32 v244, s0, 18
	s_nop 1
	v_writelane_b32 v244, s1, 19
; #define LAS __attribute__((address_space(3)))
; template <class Epi, class Sched, bool ALIGN_EPI = false, bool SP2 = false>
; __device__ __forceinline__ void gemm_phase(LAS unsigned char* lds, const Gemm g, const Sched& S, const Epi& E) {
;     int tid = threadIdx.x; asm volatile("" : "+v"(tid));
;     const int wid = __builtin_amdgcn_readfirstlane(tid >> 6), lane = tid & 63, wr = wid >> 2, wc = wid & 3, fr = lane & 15, fq = lane >> 4;
;     const int K = g.K, nt = g.nt;
;     unsigned voffA[2], voffB[2];
; #pragma unroll
;     for (int i = 0; i < 2; ++i) { int R, C; stage_rc(tid * 16 + i * 8192, R, C); const int Rb = Epi::PERM ? ((R & ~31) + perm32(R & 31)) : R;
;         voffA[i] = (unsigned)(R * K + C) * 2u; voffB[i] = (unsigned)(Rb * K + C) * 2u; }
;     const size_t kstep = (size_t)(BK * 2);
;     const size_t hstep = (size_t)HALF * K * 2;
;     const size_t tstep = 2 * hstep;
;     const unsigned ldsw = (unsigned)wid * 1024u;
;     const int aoff = lds_byte(wr * 64 + fr, fq * 8), boff = lds_byte(wc * 32 + fr, fq * 8);
;     ...
;     Unit cur, nxt; int ui = 0;
;     if (!S.next(0, cur)) return;
;     f32x4 acc[2][2][4][2];
; #pragma unroll
;     for (int a = 0; a < 2; ++a)
; #pragma unroll
;         for (int b = 0; b < 2; ++b)
; #pragma unroll
;             for (int m = 0; m < 4; ++m)
; #pragma unroll
;                 for (int n = 0; n < 2; ++n) acc[a][b][m][n] = (f32x4){0.f, 0.f, 0.f, 0.f};
;     bf16x8 At[4][2], B0[2][2], B1[2][2];
;     const char* cA = (const char*)g.A + (size_t)cur.pm * tstep + cur.kb; const char* cB = (const char*)g.Bt + (size_t)cur.pn * tstep + cur.kb;
;     S.a_ready(cur);
;     float sv[8];
	s_lshl_b64 s[0:1], s[22:23], 20
	v_writelane_b32 v244, s0, 20
	s_nop 1
	v_writelane_b32 v244, s1, 21
	s_mov_b32 s0, s4
	v_writelane_b32 v244, s0, 22
	s_nop 1
	v_writelane_b32 v244, s1, 23
	s_lshl_b64 s[0:1], s[4:5], 10
	v_writelane_b32 v244, s0, 24
	s_nop 1
	v_writelane_b32 v244, s1, 25
	s_add_u32 s0, s8, 0x80000
	v_writelane_b32 v244, s8, 26
	s_addc_u32 s1, s9, 0
	s_ashr_i32 s27, s26, 31
	v_writelane_b32 v244, s9, 27
	v_writelane_b32 v244, s0, 28
	s_nop 1
	v_writelane_b32 v244, s1, 29
	s_mul_i32 s1, s26, 0x2c0000
	v_writelane_b32 v244, s2, 30
	s_ashr_i32 s2, s2, 31
	s_mul_hi_i32 s0, s26, 0x2c0000
	s_add_u32 s4, s6, s1
	s_addc_u32 s5, s7, s0
	v_writelane_b32 v244, s2, 31
	s_add_u32 s0, s4, 0x160000
	v_writelane_b32 v244, s4, 32
	s_addc_u32 s1, s5, 0
	s_cmpk_lt_i32 s65, 0x440
	v_writelane_b32 v244, s5, 33
	s_cselect_b32 s8, s11, s10
	v_writelane_b32 v244, s0, 34
	s_cselect_b32 s4, s12, s16
	s_ashr_i32 s9, s8, 31
	v_writelane_b32 v244, s1, 35
	s_lshl_b64 s[0:1], s[8:9], 20
	s_add_u32 s10, s72, s0
	s_mov_b32 s0, s4
	s_addc_u32 s11, s73, s1
	s_ashr_i32 s5, s4, 31
	v_writelane_b32 v244, s0, 36
	s_mov_b32 s2, s28
	s_nop 0
	v_writelane_b32 v244, s1, 37
	s_lshl_b64 s[0:1], s[4:5], 20
	v_writelane_b32 v244, s0, 38
	s_nop 1
	v_writelane_b32 v244, s1, 39
	s_mov_b32 s0, s8
	v_writelane_b32 v244, s0, 40
	s_nop 1
	v_writelane_b32 v244, s1, 41
	s_lshl_b64 s[0:1], s[8:9], 10
	v_writelane_b32 v244, s0, 42
	s_nop 1
	v_writelane_b32 v244, s1, 43
	s_add_u32 s0, s10, 0x80000
	v_writelane_b32 v244, s10, 44
	s_addc_u32 s1, s11, 0
	s_ashr_i32 s29, s28, 31
	v_writelane_b32 v244, s11, 45
	v_writelane_b32 v244, s0, 46
	s_lshl_b64 s[4:5], s[28:29], 20
	s_nop 0
	v_writelane_b32 v244, s1, 47
	s_mov_b32 s0, s26
	v_writelane_b32 v244, s0, 48
	s_nop 1
	v_writelane_b32 v244, s1, 49
	v_writelane_b32 v244, s2, 50
	s_lshl_b64 s[0:1], s[26:27], 20
	s_nop 0
	v_writelane_b32 v244, s3, 51
	v_writelane_b32 v244, s4, 52
	s_mov_b32 s2, 0x16000
	s_nop 0
	v_writelane_b32 v244, s5, 53
	s_add_u32 s4, s14, s0
	s_mul_i32 s0, s21, s20
	s_mul_i32 s0, s0, s64
	s_addc_u32 s5, s15, s1
	v_writelane_b32 v244, s0, 54
	s_add_u32 s0, s4, 0x80000
	v_writelane_b32 v244, s4, 55
	s_addc_u32 s1, s5, 0
	s_nop 0
	v_writelane_b32 v244, s5, 56
	v_writelane_b32 v244, s0, 57
	s_nop 1
	v_writelane_b32 v244, s1, 58
	s_mul_i32 s0, s13, 0x2c0000
	s_add_u32 s0, s0, s30
	s_addc_u32 s1, 0, s31
	s_add_u32 s0, s98, s0
	s_addc_u32 s1, s99, s1
	v_writelane_b32 v244, s30, 59
	s_add_u32 s0, s0, 0x22e60080
	v_writelane_b32 v244, s31, 60
	s_addc_u32 s1, s1, 0
	v_writelane_b32 v244, s0, 61
	s_ashr_i32 s67, s66, 31
	s_lshl_b64 s[4:5], s[66:67], 13
	v_writelane_b32 v244, s1, 62
	v_readlane_b32 s1, v247, 36
	s_addk_i32 s1, 0x4000
	s_lshl_b32 s0, s13, 20
	v_writelane_b32 v244, s1, 63
	s_lshl_b32 s1, s65, 4
	v_writelane_b32 v246, s1, 0
	s_lshl_b32 s1, s20, 4
	v_writelane_b32 v246, s1, 1
	v_writelane_b32 v246, s4, 2
	s_nop 1
	v_writelane_b32 v246, s5, 3
	s_lshl_b64 s[4:5], s[66:67], 2
	v_writelane_b32 v246, s4, 4
	s_nop 1
	v_writelane_b32 v246, s5, 5
	s_lshl_b64 s[4:5], s[66:67], 12
	s_add_u32 s0, s0, s17
	s_addc_u32 s1, 0, s18
	v_writelane_b32 v246, s4, 6
	s_add_u32 s0, s98, s0
	s_addc_u32 s1, s99, s1
	v_writelane_b32 v246, s5, 7
	v_writelane_b32 v246, s17, 8
	s_add_u32 s0, s0, 0x27380080
	v_writelane_b32 v246, s18, 9
	s_addc_u32 s1, s1, 0
	v_writelane_b32 v246, s0, 10
	s_movk_i32 s18, 0x2200
	s_nop 0
	v_writelane_b32 v246, s1, 11
	s_mul_i32 s0, s3, 0x2c0000
	v_writelane_b32 v246, s0, 12
	s_add_i32 s0, 0, 0x20000
	v_writelane_b32 v246, s0, 13
	s_add_i32 s0, 0, 0x22000
	v_writelane_b32 v246, s0, 14
	s_add_i32 s0, 0, 0x22004
	v_writelane_b32 v246, s0, 15
	s_add_i32 s0, 0, 0x11400
	v_writelane_b32 v246, s0, 16
	s_add_i32 s0, 0, 0x7000
	v_writelane_b32 v246, s0, 17
	s_mov_b32 s1, 0
	s_mov_b32 s0, s20
	v_writelane_b32 v246, s0, 18
	s_mov_b32 s3, 0x2aaaaaab
	s_nop 0
	v_writelane_b32 v246, s1, 19
	v_writelane_b32 v246, s66, 20
	s_nop 1
	v_writelane_b32 v246, s67, 21
	v_writelane_b32 v246, s65, 22
	v_writelane_b32 v246, s74, 23
	s_nop 1
	v_writelane_b32 v246, s75, 24
	v_writelane_b32 v246, s80, 25
	s_nop 1
	v_writelane_b32 v246, s81, 26
	v_writelane_b32 v246, s82, 27
	s_nop 1
	v_writelane_b32 v246, s83, 28
	s_branch .LBB0_119

; __device__ __forceinline__ unsigned cvt_pk_bf16(float lo, float hi) { unsigned r; asm volatile("v_cvt_pk_bf16_f32 %0, %1, %2" : "=v"(r) : "v"(lo), "v"(hi)); return r; }
;     __device__ __forceinline__ void operator()(const f32x4 (&acc)[2][2][4][2], const Unit& u, int wr, int wc, int fr, int fq, const float (&sv)[8]) const {
;         const int row0 = u.pm * BM + wr * 64 + fr, col0 = u.pn * BM + wc * 32 + 8 * fq;
; #pragma unroll
;         for (int ai = 0; ai < 2; ++ai)
; #pragma unroll
;             for (int m = 0; m < 4; ++m) {
;                 const int row = row0 + ai * HALF + m * 16;
;                 const float rinv = __builtin_amdgcn_rsqf(sv[ai * 4 + m] * (1.f / DM) + EPS);
;                 bf16_t* rowp = O + (size_t)row * ldc + col0;
; #pragma unroll
;                 for (int bj = 0; bj < 2; ++bj) { const f32x4 v0 = acc[ai][bj][m][0] * rinv, v1 = acc[ai][bj][m][1] * rinv;
;                     u32x4 w; w.x = cvt_pk_bf16(v0[0], v0[1]); w.y = cvt_pk_bf16(v0[2], v0[3]); w.z = cvt_pk_bf16(v1[0], v1[1]); w.w = cvt_pk_bf16(v1[2], v1[3]);
;                     *(u32x4*)(rowp + bj * HALF) = w; }
;             }
;     }
.LBB0_365:
	s_lshl_b32 s13, s48, 10
	s_and_b32 s13, s13, 0x400
	v_add_u32_e32 v140, s13, v151
	ds_read2_b32 v[154:155], v140 offset1:16
	ds_read2_b32 v[156:157], v140 offset0:32 offset1:48
	ds_read2_b32 v[146:147], v140 offset0:128 offset1:144
	ds_read2_b32 v[140:141], v140 offset0:160 offset1:176
	v_lshl_or_b32 v144, s46, 8, v150
	s_waitcnt lgkmcnt(0)
	v_fmamk_f32 v142, v154, 0x3a000000, v218
	v_rsq_f32_e32 v154, v142
	v_lshl_add_u32 v153, s47, 8, v148
	v_ashrrev_i32_e32 v145, 31, v144
	v_mov_b64_e32 v[142:143], s[6:7]
	v_mad_i64_i32 v[158:159], s[24:25], v153, s18, v[142:143]
	v_lshlrev_b64 v[144:145], 1, v[144:145]
	v_lshl_add_u64 v[158:159], v[158:159], 0, v[144:145]
	v_pk_mul_f32 v[126:127], v[126:127], v[154:155] op_sel_hi:[1,0]
	v_pk_mul_f32 v[124:125], v[124:125], v[154:155] op_sel_hi:[1,0]
	v_pk_mul_f32 v[160:161], v[122:123], v[154:155] op_sel_hi:[1,0]
	v_pk_mul_f32 v[122:123], v[120:121], v[154:155] op_sel_hi:[1,0]
	v_cvt_pk_bf16_f32 v120, v124, v125
	v_cvt_pk_bf16_f32 v121, v126, v127
	v_pk_mul_f32 v[116:117], v[116:117], v[154:155] op_sel_hi:[1,0]
	v_cvt_pk_bf16_f32 v122, v122, v123
	v_cvt_pk_bf16_f32 v123, v160, v161
	global_store_dwordx4 v[158:159], v[120:123], off
	v_pk_mul_f32 v[118:119], v[118:119], v[154:155] op_sel_hi:[1,0]
	s_andn2_b64 vcc, exec, s[36:37]
	v_pk_mul_f32 v[120:121], v[110:111], v[154:155] op_sel_hi:[1,0]
	v_pk_mul_f32 v[110:111], v[108:109], v[154:155] op_sel_hi:[1,0]
	v_cvt_pk_bf16_f32 v108, v116, v117
	v_cvt_pk_bf16_f32 v109, v118, v119
	s_nop 0
	v_cvt_pk_bf16_f32 v110, v110, v111
	v_cvt_pk_bf16_f32 v111, v120, v121
	global_store_dwordx4 v[158:159], v[108:111], off offset:256
	s_nop 1
	v_fmamk_f32 v108, v155, 0x3a000000, v218
	v_rsq_f32_e32 v108, v108
	v_or_b32_e32 v109, 16, v153
	v_mad_i64_i32 v[110:111], s[24:25], v109, s18, v[142:143]
	v_lshl_add_u64 v[110:111], v[110:111], 0, v[144:145]
	v_pk_mul_f32 v[114:115], v[114:115], v[108:109] op_sel_hi:[1,0]
	v_pk_mul_f32 v[112:113], v[112:113], v[108:109] op_sel_hi:[1,0]
	v_pk_mul_f32 v[116:117], v[106:107], v[108:109] op_sel_hi:[1,0]
	v_pk_mul_f32 v[106:107], v[104:105], v[108:109] op_sel_hi:[1,0]
	v_cvt_pk_bf16_f32 v104, v112, v113
	v_cvt_pk_bf16_f32 v105, v114, v115
	v_pk_mul_f32 v[100:101], v[100:101], v[108:109] op_sel_hi:[1,0]
	v_cvt_pk_bf16_f32 v106, v106, v107
	v_cvt_pk_bf16_f32 v107, v116, v117
	global_store_dwordx4 v[110:111], v[104:107], off
	v_pk_mul_f32 v[102:103], v[102:103], v[108:109] op_sel_hi:[1,0]
	s_nop 0
	v_pk_mul_f32 v[104:105], v[94:95], v[108:109] op_sel_hi:[1,0]
	v_pk_mul_f32 v[94:95], v[92:93], v[108:109] op_sel_hi:[1,0]
	v_cvt_pk_bf16_f32 v92, v100, v101
	v_cvt_pk_bf16_f32 v93, v102, v103
	s_nop 0
	v_cvt_pk_bf16_f32 v94, v94, v95
	v_cvt_pk_bf16_f32 v95, v104, v105
	global_store_dwordx4 v[110:111], v[92:95], off offset:256
	s_nop 1
	v_fmamk_f32 v92, v156, 0x3a000000, v218
	v_rsq_f32_e32 v92, v92
	v_or_b32_e32 v93, 32, v153
	v_mad_i64_i32 v[94:95], s[24:25], v93, s18, v[142:143]
	v_lshl_add_u64 v[94:95], v[94:95], 0, v[144:145]
	v_pk_mul_f32 v[98:99], v[98:99], v[92:93] op_sel_hi:[1,0]
	v_pk_mul_f32 v[96:97], v[96:97], v[92:93] op_sel_hi:[1,0]
	v_pk_mul_f32 v[100:101], v[90:91], v[92:93] op_sel_hi:[1,0]
	v_pk_mul_f32 v[90:91], v[88:89], v[92:93] op_sel_hi:[1,0]
	v_cvt_pk_bf16_f32 v88, v96, v97
	v_cvt_pk_bf16_f32 v89, v98, v99
	v_pk_mul_f32 v[84:85], v[84:85], v[92:93] op_sel_hi:[1,0]
	v_cvt_pk_bf16_f32 v90, v90, v91
	v_cvt_pk_bf16_f32 v91, v100, v101
	global_store_dwordx4 v[94:95], v[88:91], off
	v_pk_mul_f32 v[86:87], v[86:87], v[92:93] op_sel_hi:[1,0]
	s_nop 0
	v_pk_mul_f32 v[88:89], v[78:79], v[92:93] op_sel_hi:[1,0]
	v_pk_mul_f32 v[78:79], v[76:77], v[92:93] op_sel_hi:[1,0]
	v_cvt_pk_bf16_f32 v76, v84, v85
	v_cvt_pk_bf16_f32 v77, v86, v87
	s_nop 0
	v_cvt_pk_bf16_f32 v78, v78, v79
	v_cvt_pk_bf16_f32 v79, v88, v89
	global_store_dwordx4 v[94:95], v[76:79], off offset:256
	s_nop 1
	v_fmamk_f32 v76, v157, 0x3a000000, v218
	v_rsq_f32_e32 v76, v76
	v_or_b32_e32 v77, 48, v153
	v_mad_i64_i32 v[78:79], s[24:25], v77, s18, v[142:143]
	v_lshl_add_u64 v[78:79], v[78:79], 0, v[144:145]
	v_pk_mul_f32 v[82:83], v[82:83], v[76:77] op_sel_hi:[1,0]
	v_pk_mul_f32 v[80:81], v[80:81], v[76:77] op_sel_hi:[1,0]
	v_pk_mul_f32 v[84:85], v[74:75], v[76:77] op_sel_hi:[1,0]
	v_pk_mul_f32 v[74:75], v[72:73], v[76:77] op_sel_hi:[1,0]
	v_cvt_pk_bf16_f32 v72, v80, v81
	v_cvt_pk_bf16_f32 v73, v82, v83
	v_pk_mul_f32 v[60:61], v[60:61], v[76:77] op_sel_hi:[1,0]
	v_cvt_pk_bf16_f32 v74, v74, v75
	v_cvt_pk_bf16_f32 v75, v84, v85
	global_store_dwordx4 v[78:79], v[72:75], off
	v_pk_mul_f32 v[62:63], v[62:63], v[76:77] op_sel_hi:[1,0]
	s_nop 0
	v_pk_mul_f32 v[72:73], v[58:59], v[76:77] op_sel_hi:[1,0]
	v_pk_mul_f32 v[58:59], v[56:57], v[76:77] op_sel_hi:[1,0]
	v_cvt_pk_bf16_f32 v56, v60, v61
	v_cvt_pk_bf16_f32 v57, v62, v63
	s_nop 0
; __device__ __forceinline__ unsigned cvt_pk_bf16(float lo, float hi) { unsigned r; asm volatile("v_cvt_pk_bf16_f32 %0, %1, %2" : "=v"(r) : "v"(lo), "v"(hi)); return r; }
;     __device__ __forceinline__ void operator()(const f32x4 (&acc)[2][2][4][2], const Unit& u, int wr, int wc, int fr, int fq, const float (&sv)[8]) const {
;         const int row0 = u.pm * BM + wr * 64 + fr, col0 = u.pn * BM + wc * 32 + 8 * fq;
; #pragma unroll
;         for (int ai = 0; ai < 2; ++ai)
; #pragma unroll
;             for (int m = 0; m < 4; ++m) {
;                 const int row = row0 + ai * HALF + m * 16;
;                 const float rinv = __builtin_amdgcn_rsqf(sv[ai * 4 + m] * (1.f / DM) + EPS);
;                 bf16_t* rowp = O + (size_t)row * ldc + col0;
; #pragma unroll
;                 for (int bj = 0; bj < 2; ++bj) { const f32x4 v0 = acc[ai][bj][m][0] * rinv, v1 = acc[ai][bj][m][1] * rinv;
;                     u32x4 w; w.x = cvt_pk_bf16(v0[0], v0[1]); w.y = cvt_pk_bf16(v0[2], v0[3]); w.z = cvt_pk_bf16(v1[0], v1[1]); w.w = cvt_pk_bf16(v1[2], v1[3]);
;                     *(u32x4*)(rowp + bj * HALF) = w; }
;             }
;     }
; template <class Epi, class Sched, bool ALIGN_EPI = false, bool SP2 = false>
; __device__ __forceinline__ void gemm_phase(LAS unsigned char* lds, const Gemm g, const Sched& S, const Epi& E) {
;     ...
;         if constexpr (!Epi::AFTER_DRAIN) { E(acc, cur, wr, wc, fr, fq, sv); S.done(cur); }
	v_cvt_pk_bf16_f32 v58, v58, v59
	v_cvt_pk_bf16_f32 v59, v72, v73
	global_store_dwordx4 v[78:79], v[56:59], off offset:256
	s_nop 1
	v_fmamk_f32 v56, v146, 0x3a000000, v218
	v_rsq_f32_e32 v56, v56
	v_add_u32_e32 v57, 0x80, v153
	v_mad_i64_i32 v[58:59], s[24:25], v57, s18, v[142:143]
	v_lshl_add_u64 v[58:59], v[58:59], 0, v[144:145]
	v_pk_mul_f32 v[54:55], v[54:55], v[56:57] op_sel_hi:[1,0]
	v_pk_mul_f32 v[52:53], v[52:53], v[56:57] op_sel_hi:[1,0]
	v_pk_mul_f32 v[60:61], v[42:43], v[56:57] op_sel_hi:[1,0]
	v_pk_mul_f32 v[42:43], v[40:41], v[56:57] op_sel_hi:[1,0]
	v_cvt_pk_bf16_f32 v40, v52, v53
	v_cvt_pk_bf16_f32 v41, v54, v55
	v_pk_mul_f32 v[52:53], v[70:71], v[56:57] op_sel_hi:[1,0]
	v_cvt_pk_bf16_f32 v42, v42, v43
	v_cvt_pk_bf16_f32 v43, v60, v61
	global_store_dwordx4 v[58:59], v[40:43], off
	v_pk_mul_f32 v[54:55], v[68:69], v[56:57] op_sel_hi:[1,0]
	s_nop 0
	v_pk_mul_f32 v[40:41], v[64:65], v[56:57] op_sel_hi:[1,0]
	v_pk_mul_f32 v[42:43], v[66:67], v[56:57] op_sel_hi:[1,0]
	v_cvt_pk_bf16_f32 v40, v40, v41
	s_nop 0
	v_cvt_pk_bf16_f32 v41, v42, v43
	v_cvt_pk_bf16_f32 v42, v54, v55
	v_cvt_pk_bf16_f32 v43, v52, v53
	global_store_dwordx4 v[58:59], v[40:43], off offset:256
	s_nop 1
	v_fmamk_f32 v40, v147, 0x3a000000, v218
	v_rsq_f32_e32 v40, v40
	v_add_u32_e32 v41, 0x90, v153
	v_mad_i64_i32 v[42:43], s[24:25], v41, s18, v[142:143]
	v_lshl_add_u64 v[42:43], v[42:43], 0, v[144:145]
	v_pk_mul_f32 v[30:31], v[30:31], v[40:41] op_sel_hi:[1,0]
	v_pk_mul_f32 v[28:29], v[28:29], v[40:41] op_sel_hi:[1,0]
	v_pk_mul_f32 v[52:53], v[26:27], v[40:41] op_sel_hi:[1,0]
	v_pk_mul_f32 v[26:27], v[24:25], v[40:41] op_sel_hi:[1,0]
	v_cvt_pk_bf16_f32 v24, v28, v29
	v_cvt_pk_bf16_f32 v25, v30, v31
	v_pk_mul_f32 v[28:29], v[50:51], v[40:41] op_sel_hi:[1,0]
	v_cvt_pk_bf16_f32 v26, v26, v27
	v_cvt_pk_bf16_f32 v27, v52, v53
	global_store_dwordx4 v[42:43], v[24:27], off
	v_pk_mul_f32 v[30:31], v[48:49], v[40:41] op_sel_hi:[1,0]
	s_nop 0
	v_pk_mul_f32 v[24:25], v[44:45], v[40:41] op_sel_hi:[1,0]
	v_pk_mul_f32 v[26:27], v[46:47], v[40:41] op_sel_hi:[1,0]
	v_cvt_pk_bf16_f32 v24, v24, v25
	s_nop 0
	v_cvt_pk_bf16_f32 v25, v26, v27
	v_cvt_pk_bf16_f32 v26, v30, v31
	v_cvt_pk_bf16_f32 v27, v28, v29
	global_store_dwordx4 v[42:43], v[24:27], off offset:256
	s_nop 1
	v_fmamk_f32 v24, v140, 0x3a000000, v218
	v_rsq_f32_e32 v24, v24
	v_add_u32_e32 v25, 0xa0, v153
	v_mad_i64_i32 v[26:27], s[24:25], v25, s18, v[142:143]
	v_lshl_add_u64 v[26:27], v[26:27], 0, v[144:145]
	v_pk_mul_f32 v[14:15], v[14:15], v[24:25] op_sel_hi:[1,0]
	v_pk_mul_f32 v[12:13], v[12:13], v[24:25] op_sel_hi:[1,0]
	v_pk_mul_f32 v[28:29], v[10:11], v[24:25] op_sel_hi:[1,0]
	v_pk_mul_f32 v[10:11], v[8:9], v[24:25] op_sel_hi:[1,0]
	v_cvt_pk_bf16_f32 v8, v12, v13
	v_cvt_pk_bf16_f32 v9, v14, v15
	v_pk_mul_f32 v[12:13], v[38:39], v[24:25] op_sel_hi:[1,0]
	v_cvt_pk_bf16_f32 v10, v10, v11
	v_cvt_pk_bf16_f32 v11, v28, v29
	global_store_dwordx4 v[26:27], v[8:11], off
	v_pk_mul_f32 v[14:15], v[36:37], v[24:25] op_sel_hi:[1,0]
	s_nop 0
	v_pk_mul_f32 v[8:9], v[32:33], v[24:25] op_sel_hi:[1,0]
	v_pk_mul_f32 v[10:11], v[34:35], v[24:25] op_sel_hi:[1,0]
	v_cvt_pk_bf16_f32 v8, v8, v9
	s_nop 0
	v_cvt_pk_bf16_f32 v9, v10, v11
	v_cvt_pk_bf16_f32 v10, v14, v15
	v_cvt_pk_bf16_f32 v11, v12, v13
	global_store_dwordx4 v[26:27], v[8:11], off offset:256
	s_nop 1
	v_fmamk_f32 v8, v141, 0x3a000000, v218
	v_rsq_f32_e32 v8, v8
	v_add_u32_e32 v9, 0xb0, v153
	v_mad_i64_i32 v[10:11], s[24:25], v9, s18, v[142:143]
	v_pk_mul_f32 v[12:13], v[2:3], v[8:9] op_sel_hi:[1,0]
	v_pk_mul_f32 v[2:3], v[0:1], v[8:9] op_sel_hi:[1,0]
	v_lshl_add_u64 v[10:11], v[10:11], 0, v[144:145]
	v_pk_mul_f32 v[6:7], v[6:7], v[8:9] op_sel_hi:[1,0]
	v_pk_mul_f32 v[4:5], v[4:5], v[8:9] op_sel_hi:[1,0]
	s_mov_b64 s[24:25], -1
	v_cvt_pk_bf16_f32 v0, v4, v5
	v_cvt_pk_bf16_f32 v1, v6, v7
	v_cvt_pk_bf16_f32 v2, v2, v3
	v_cvt_pk_bf16_f32 v3, v12, v13
	global_store_dwordx4 v[10:11], v[0:3], off
	v_pk_mul_f32 v[4:5], v[22:23], v[8:9] op_sel_hi:[1,0]
	v_pk_mul_f32 v[6:7], v[20:21], v[8:9] op_sel_hi:[1,0]
	v_pk_mul_f32 v[2:3], v[18:19], v[8:9] op_sel_hi:[1,0]
	v_pk_mul_f32 v[0:1], v[16:17], v[8:9] op_sel_hi:[1,0]
	s_nop 0
	v_cvt_pk_bf16_f32 v0, v0, v1
	v_cvt_pk_bf16_f32 v1, v2, v3
	v_cvt_pk_bf16_f32 v2, v6, v7
	v_cvt_pk_bf16_f32 v3, v4, v5
	global_store_dwordx4 v[10:11], v[0:3], off offset:256
	s_cmp_lg_u32 s48, 3
	s_cbranch_scc1 .Lpw_ea_skip
	s_waitcnt vmcnt(0)
	s_barrier
	v_cmp_eq_u32_e32 vcc, 0, v216
	s_and_saveexec_b64 s[100:101], vcc
	s_cbranch_execz .Lpw_ea_done
	buffer_wbl2 sc1
	v_readlane_b32 vcc_lo, v246, 29
	s_lshl_b32 vcc_lo, vcc_lo, 6
	s_and_b32 vcc_hi, s65, 7
	s_lshl_b32 vcc_hi, vcc_hi, 2
	s_add_u32 vcc_lo, vcc_lo, vcc_hi
	s_add_u32 vcc_lo, vcc_lo, 0x83800
	v_mov_b32_e32 v2, vcc_lo
	v_mov_b32_e32 v4, 1
	s_waitcnt vmcnt(0)
	global_atomic_add v2, v4, s[98:99]

; #define PG8_SS_DMA(u, buf) do { if constexpr (Epi::PREF) { if (wid == 0) __builtin_amdgcn_global_load_lds((const unsigned*)(E.ss + (size_t)(u).pm * BM + 4 * lane), (LAS unsigned*)(lds + STAGE_BYTES + (buf) * 1024), 16, 0, 0); } } while (0)
; template <class Epi, class Sched, bool ALIGN_EPI = false, bool SP2 = false>
; __device__ __forceinline__ void gemm_phase(LAS unsigned char* lds, const Gemm g, const Sched& S, const Epi& E) {
;     ...
;         if constexpr (!Epi::AFTER_DRAIN) { E(acc, cur, wr, wc, fr, fq, sv); S.done(cur); }
;         if (!has_next) break;
; #pragma unroll
;         for (int a = 0; a < 2; ++a)
; #pragma unroll
;             for (int b = 0; b < 2; ++b)
; #pragma unroll
;                 for (int m = 0; m < 4; ++m)
; #pragma unroll
;                     for (int n = 0; n < 2; ++n) acc[a][b][m][n] = (f32x4){0.f, 0.f, 0.f, 0.f};
;         cur = nxt; cA = nA; cB = nB; ++ui;
;         PG8_SS_DMA(cur, ui & 1);
.Lpw_ea_skip:
	s_andn2_b64 vcc, exec, s[36:37]
	s_cbranch_vccnz .LBB0_355
	s_andn2_b64 vcc, exec, s[0:1]
	s_cbranch_vccnz .LBB0_368
	s_lshl_b32 s13, s45, 10
	s_and_b32 s13, s13, 0x400
	s_add_i32 s13, s13, 0
	s_lshl_b64 s[24:25], s[10:11], 10
	s_add_i32 m0, s13, 0x20000
	v_lshl_add_u64 v[0:1], v[134:135], 0, s[24:25]
	global_load_lds_dwordx4 v[0:1], off

; #define PG8_WAIT_V(n) asm volatile("s_waitcnt vmcnt(" #n ")" ::: "memory")
; #define PG8_BAR __builtin_amdgcn_s_barrier()
; #define GRID_BAR() xcd_barrier(xbar)
; template <class Epi, class Sched, bool ALIGN_EPI = false, bool SP2 = false>
; __device__ __forceinline__ void gemm_phase(LAS unsigned char* lds, const Gemm g, const Sched& S, const Epi& E) {
;     ...
;     PG8_WAIT_V(0);
;     if constexpr (!ALIGN_EPI) { if (wr == 0) PG8_BAR; }
;     PG8_BAR;
; __global__ void __launch_bounds__(512, 2) fwd_megakernel(Params p) {
;     ...
;             GRID_BAR();
.LBB0_371:
	s_waitcnt vmcnt(0)
	s_waitcnt vmcnt(0) lgkmcnt(0)
	s_barrier
	s_mov_b32 s101, 0
	s_cmpk_lt_u32 s65, 224
	s_cbranch_scc1 .Lpw_bar2
	v_cmp_eq_u32_e32 vcc, 0, v216
	s_and_saveexec_b64 s[100:101], vcc
	s_cbranch_execz .Lpw_gw_done
	v_readlane_b32 vcc_lo, v246, 29
	s_lshl_b32 vcc_lo, vcc_lo, 6
	s_add_u32 vcc_lo, vcc_lo, 0x83800
	s_and_b32 vcc_hi, s65, 7
	s_lshl_b32 vcc_hi, vcc_hi, 2
	s_add_u32 vcc_lo, vcc_lo, vcc_hi
	v_mov_b32_e32 v2, vcc_lo
	s_mov_b32 vcc_hi, 0

; __device__ __forceinline__ unsigned xb_ld(unsigned* p)              { return __hip_atomic_load(p, __ATOMIC_RELAXED, __HIP_MEMORY_SCOPE_AGENT); }
; __device__ __forceinline__ unsigned xb_add(unsigned* p, unsigned v) { return __hip_atomic_fetch_add(p, v, __ATOMIC_RELAXED, __HIP_MEMORY_SCOPE_AGENT); }
; #define XB_SPIN(cond, bar) do { unsigned _sp = 0; while (cond) { __builtin_amdgcn_s_sleep(1); \
;     if ((++_sp & 255u) == 0u) { if (xb_ld(&(bar)[XB_TMO])) break; if (_sp > XB_SPIN_CAP) { atomicAdd(&(bar)[XB_TMO], 1u); break; } } } } while (0)
; #define GRID_BAR() xcd_barrier(xbar)
; __device__ __forceinline__ void xcd_barrier(const XcdBarrier& b) {
;     asm volatile("s_waitcnt vmcnt(0)" ::: "memory");
;     __syncthreads();
;     if (threadIdx.x == 0) {
;         unsigned* bar = b.bar;
;         __builtin_amdgcn_s_waitcnt(0);
;         unsigned nloc = b.st[0], nx = b.st[1];
;         if (nloc == 0u) { xcd_barrier_complete(bar, b.x, nloc, nx); b.st[0] = nloc; b.st[1] = nx; }
;         const unsigned old = xb_add(&bar[XB_XSUB(b.x)], 1u);
;         const unsigned gen = old / nloc;
;         if (old + 1u == (gen + 1u) * nloc) {
;             __builtin_amdgcn_fence(__ATOMIC_RELEASE, "agent");
;             asm volatile("s_waitcnt vmcnt(0)" ::: "memory");
;             const unsigned og = xb_add(&bar[XB_TOP], 1u);
;             const unsigned tg = og / nx;
;             if (og + 1u == (tg + 1u) * nx) xb_add(&bar[XB_TOPGEN], 1u);
;             else XB_SPIN(xb_ld(&bar[XB_TOPGEN]) == tg, bar);
;             __builtin_amdgcn_fence(__ATOMIC_ACQUIRE, "agent");
;             xb_add(&bar[XB_XGEN(b.x)], 1u);
;             asm volatile("s_waitcnt vmcnt(0)" ::: "memory");
;         } else {
;             XB_SPIN(xb_ld(&bar[XB_XGEN(b.x)]) == gen, bar);
;             __builtin_amdgcn_fence(__ATOMIC_ACQUIRE, "agent");
;             asm volatile("s_waitcnt vmcnt(0)" ::: "memory");
;         }
;     }
;     __syncthreads();
; }
; __global__ void __launch_bounds__(512, 2) fwd_megakernel(Params p) {
;     ...
;             GRID_BAR();
.Lpw_gw_done:
	s_or_b64 exec, exec, s[100:101]
	s_barrier
	v_readlane_b32 s100, v244, 9
	s_sub_u32 s100, s100, 32
	v_writelane_b32 v244, s100, 9
	s_mov_b32 s100, 4
	s_nop 0
	v_writelane_b32 v244, s100, 10
	s_mov_b32 s101, 1
	s_branch .Lpw_mixer_entry
.Lpw_bar2:
	s_mov_b64 s[0:1], exec
	v_readlane_b32 s4, v247, 0
	v_readlane_b32 s5, v247, 1
	s_and_b64 s[4:5], s[0:1], s[4:5]
	s_xor_b64 s[0:1], s[4:5], s[0:1]
	s_mov_b64 exec, s[4:5]
	s_cbranch_execz .LBB0_420
	v_readlane_b32 s4, v246, 14
	s_waitcnt vmcnt(0) expcnt(0) lgkmcnt(0)
	s_nop 0
	v_mov_b32_e32 v0, s4
	ds_read_b32 v2, v0
	v_readlane_b32 s4, v246, 15
	s_waitcnt lgkmcnt(0)
	v_cmp_ne_u32_e32 vcc, 0, v2
	v_mov_b32_e32 v0, s4
	ds_read_b32 v0, v0
	s_cbranch_vccnz .LBB0_387
	s_mov_b32 s12, 1
	s_branch .LBB0_375

; #define LAS __attribute__((address_space(3)))
; __device__ __forceinline__ void mixer_mid(const Params& p, LAS unsigned char* lds, int G, int layer) {
;     int tid = threadIdx.x; asm volatile("" : "+v"(tid));
;     const int lane = tid & 63, wave = __builtin_amdgcn_readfirstlane(tid >> 6);
;     LAS float* vt = (LAS float*)lds;
;     LAS float* cb = (LAS float*)(lds + VROWS * CH * 4);
;     const bf16_t* z = (const bf16_t*)(p.ws + WS_ACT);
;     bf16_t* cat = (bf16_t*)(p.ws + WS_CAT);
;     const float* caw = p.in[I_CAW] + layer * 3 * DA;
;     const float* cbw = p.in[I_CBW] + layer * 31 * DB;
;     const float* cbb = p.in[I_CBB] + layer * DB;
;     const float* lng = p.in[I_LNG] + layer * DB;
;     const float* lnb = p.in[I_LNB] + layer * DB;
;     constexpr int NCH = MT / TOK, NCH_X = NCH / 8;
;     static_assert(NCH % 8 == 0, "chunks divide over the XCDs");
;     const int mx_x = (G % 8 == 0) ? (int)(blockIdx.x & 7) : 0, mx_r = (G % 8 == 0) ? (int)(blockIdx.x >> 3) : (int)blockIdx.x, mx_n = (G % 8 == 0) ? G / 8 : G, mx_tot = (G % 8 == 0) ? NCH_X : NCH;
;     u32x4 ra[5], rg[5]; bool preloaded = false;
;     ...
;     for (int ci = mx_r; ci < mx_tot; ci += mx_n) {
.Lpw_mixer_entry:
	v_readlane_b32 s0, v244, 11
	v_mov_b32_e32 v92, v216
	v_readlane_b32 s1, v244, 12
	s_waitcnt lgkmcnt(0)
	s_barrier
	s_and_b64 vcc, exec, s[0:1]
	v_readfirstlane_b32 s8, v92
	s_cbranch_vccz .LBB0_539
	v_readlane_b32 s44, v247, 18
	v_and_b32_e32 v3, 64, v217
	s_and_b64 s[0:1], s[40:41], exec
	v_readlane_b32 s50, v247, 24
	v_readlane_b32 s51, v247, 25
	v_add_u32_e32 v3, 64, v3
	v_xor_b32_e32 v4, 1, v217
	s_cselect_b32 s0, 0x2400, 0
	s_mov_b64 s[42:43], s[50:51]
	v_cmp_lt_i32_e32 vcc, v4, v3
	s_add_u32 s24, s42, s0
	s_addc_u32 s25, s43, 0
	v_cndmask_b32_e32 v4, v217, v4, vcc
	v_lshlrev_b32_e32 v171, 2, v4
	v_xor_b32_e32 v4, 2, v217
	v_readlane_b32 s45, v247, 19
	v_readlane_b32 s46, v247, 20
	v_readlane_b32 s47, v247, 21
	v_readlane_b32 s48, v247, 22
	v_readlane_b32 s49, v247, 23
	v_readlane_b32 s52, v247, 26
	v_readlane_b32 s53, v247, 27
	s_and_b64 s[0:1], s[40:41], exec
	v_cmp_lt_i32_e32 vcc, v4, v3
	v_readlane_b32 s54, v247, 28
	v_readlane_b32 s55, v247, 29
	v_readlane_b32 s56, v247, 30
	v_readlane_b32 s57, v247, 31
	v_readlane_b32 s58, v247, 32
	v_readlane_b32 s59, v247, 33
	s_mov_b64 s[44:45], s[52:53]
	s_cselect_b32 s0, 0x17400, 0
	v_cndmask_b32_e32 v4, v217, v4, vcc
	s_add_u32 s26, s44, s0
	v_lshlrev_b32_e32 v172, 2, v4
	v_xor_b32_e32 v4, 4, v217
	s_addc_u32 s27, s45, 0
	v_cmp_lt_i32_e32 vcc, v4, v3
	s_and_b64 s[0:1], s[40:41], exec
	s_mov_b64 s[46:47], s[54:55]
	v_cndmask_b32_e32 v4, v217, v4, vcc
	s_cselect_b32 s9, 0xc00, 0
	v_lshlrev_b32_e32 v173, 2, v4
	v_xor_b32_e32 v4, 8, v217
	s_add_u32 s28, s46, s9
	v_cmp_lt_i32_e32 vcc, v4, v3
	s_addc_u32 s29, s47, 0
	s_and_b64 s[0:1], s[40:41], exec
	v_cndmask_b32_e32 v4, v217, v4, vcc
	v_lshlrev_b32_e32 v174, 2, v4
	v_xor_b32_e32 v4, 16, v217
	s_cselect_b32 s0, 8, 0
	v_cmp_lt_i32_e32 vcc, v4, v3
	v_writelane_b32 v246, s0, 35
	s_mov_b32 s0, 0x2100c00
	v_cndmask_b32_e32 v4, v217, v4, vcc
	s_mov_b64 s[48:49], s[56:57]
	s_cselect_b32 s0, s0, 0x2100000
	v_lshlrev_b32_e32 v175, 2, v4
	v_xor_b32_e32 v4, 32, v217
	v_writelane_b32 v246, s0, 36
	s_cselect_b32 s0, 2, 0
	s_add_u32 s4, s48, s9
	v_cmp_lt_i32_e32 vcc, v4, v3
	s_mov_b64 s[50:51], s[58:59]
	s_addc_u32 s5, s49, 0
	v_lshlrev_b32_e32 v93, 3, v92
	v_cndmask_b32_e32 v3, v217, v4, vcc
	v_writelane_b32 v246, s0, 37
	s_add_u32 s0, s50, s9
	v_lshlrev_b32_e32 v176, 2, v3
	v_bfe_u32 v3, v93, 7, 2
	s_addc_u32 s1, s51, 0
	v_and_b32_e32 v1, 63, v92
	s_ashr_i32 s8, s8, 5
	v_lshlrev_b32_e64 v177, v3, 2
	v_mul_hi_i32 v3, v92, s3
	s_and_b32 s84, s8, -2
	v_lshlrev_b32_e32 v188, 3, v1
	v_readlane_b32 s8, v246, 16
	v_lshrrev_b32_e32 v4, 31, v3
	v_ashrrev_i32_e32 v3, 3, v3
	s_movk_i32 s9, 0x180
	v_add_u32_e32 v170, s8, v188
	s_movk_i32 s8, 0x8a0
	v_add_u32_e32 v94, v3, v4
	s_movk_i32 s10, 0xffd0
	v_add_u32_e32 v6, 0x200, v92
	v_cmp_gt_i32_e64 s[36:37], s9, v92
	v_cmp_gt_i32_e64 s[38:39], s8, v92
	v_mad_u64_u32 v[4:5], s[8:9], v94, s10, v[92:93]
	v_mul_hi_i32 v3, v6, s3
	v_lshrrev_b32_e32 v5, 31, v3
	v_ashrrev_i32_e32 v3, 3, v3
	v_add_u32_e32 v10, 0x400, v92
	s_movk_i32 s8, 0x6a0
	v_add_u32_e32 v100, v3, v5
	v_mul_hi_i32 v3, v10, s3
	v_cmp_gt_i32_e64 s[40:41], s8, v92
	v_mad_u64_u32 v[8:9], s[8:9], v100, s10, v[6:7]
	v_lshrrev_b32_e32 v5, 31, v3
	v_ashrrev_i32_e32 v3, 3, v3
	v_add_u32_e32 v14, 0x600, v92
	s_movk_i32 s8, 0x4a0
	v_add_u32_e32 v106, v3, v5
	v_mul_hi_i32 v3, v14, s3
	v_cmp_gt_i32_e64 s[42:43], s8, v92
	v_mad_u64_u32 v[12:13], s[8:9], v106, s10, v[10:11]
	v_lshrrev_b32_e32 v5, 31, v3
	v_ashrrev_i32_e32 v3, 3, v3
	v_add_u32_e32 v18, 0x800, v92
	s_movk_i32 s8, 0x2a0
	v_add_u32_e32 v112, v3, v5
	v_mul_hi_i32 v3, v18, s3
	v_cmp_gt_i32_e64 s[44:45], s8, v92
	v_mad_u64_u32 v[16:17], s[8:9], v112, s10, v[14:15]
	v_lshrrev_b32_e32 v5, 31, v3
	v_ashrrev_i32_e32 v3, 3, v3
	s_movk_i32 s8, 0xa0
	v_add_u32_e32 v118, v3, v5
	v_cmp_gt_i32_e64 s[46:47], s8, v92
	v_mad_u64_u32 v[18:19], s[8:9], v118, s10, v[18:19]
	v_lshlrev_b32_e32 v96, 3, v4
	s_movk_i32 s10, 0x600
	s_movk_i32 s8, 0x2ff
	v_ashrrev_i32_e32 v97, 31, v96
	v_mul_lo_u32 v3, v94, s10
; #define MIX_VLOAD(hc_, row0_) do { _Pragma("unroll") for (int i = 0; i < 5; ++i) { const int it = tid + 512 * i; if (it < VROWS * (CH / 8)) { const int j = it / (CH / 8), cl = (it - j * (CH / 8)) * 8; \
;             const bf16_t* zr = z + ((ptrdiff_t)(row0_) - HALO + j) * DIN + (hc_) * CH + cl; ra[i] = *(const u32x4*)(zr + 2304); rg[i] = *(const u32x4*)(zr + 3072); } } } while (0)
; __device__ __forceinline__ void mixer_mid(const Params& p, LAS unsigned char* lds, int G, int layer) {
;     ...
;     for (int ci = mx_r; ci < mx_tot; ci += mx_n) {
;         const int ch = mx_x * NCH_X + ci;
;         const bool samp = ch >= MP / TOK;
;         int seq, l0, L;
;         if (!samp) { seq = ch >> 9; l0 = (ch & 511) * TOK; L = 8192; } else { const int cs = ch - MP / TOK; seq = cs >> 2; l0 = (cs & 3) * TOK; L = 64; }
;         const int row0 = ch * TOK;
;         const bool lastc = (l0 + TOK == L), edge = (l0 < 32);
;         const float* hist_a = p.in[I_CA] + (size_t)(layer * 8 + seq) * 2 * DA;
;         const float* hist_b = p.in[I_CB] + (size_t)(layer * 8 + seq) * 30 * DB;
;         const float* hist_p = p.in[I_CP] + (size_t)(layer * 8 + seq) * 15 * DC;
;         float* out_a = p.out + (samp ? OFF_A_S + (layer * 8 + seq) * 2 * DA : OFF_A_P + (layer * 2 + seq) * 2 * DA);
;         float* out_b = p.out + (samp ? OFF_B_S + (layer * 8 + seq) * 30 * DB : OFF_B_P + (layer * 2 + seq) * 30 * DB);
;         float* out_p = p.out + (samp ? OFF_P_S + (layer * 8 + seq) * 15 * DC : OFF_P_P + (layer * 2 + seq) * 15 * DC);
;         if (!preloaded) MIX_VLOAD(0, row0);
;         preloaded = false;
; #pragma unroll 1
;         for (int hc = 0; hc < 2; ++hc) {
; #pragma unroll
;             for (int i = 0; i < 5; ++i) { const int it = tid + 512 * i; if (it < VROWS * (CH / 8)) { const int j = it / (CH / 8), cl = (it - j * (CH / 8)) * 8, c8 = hc * CH + cl;
	v_lshlrev_b32_e32 v4, 5, v4
	v_cmp_lt_i32_e64 s[8:9], s8, v92
	v_lshl_add_u64 v[98:99], v[96:97], 1, s[6:7]
	v_add3_u32 v97, 0, v3, v4
	v_writelane_b32 v246, s8, 38
	v_add_u32_e32 v3, -16, v94
	v_lshlrev_b32_e32 v102, 3, v8
	v_writelane_b32 v246, s9, 39
	v_mad_u64_u32 v[124:125], s[8:9], v3, s33, 0
	s_movk_i32 s8, 0xff
	v_ashrrev_i32_e32 v103, 31, v102
	v_mul_lo_u32 v3, v100, s10
	v_lshlrev_b32_e32 v4, 5, v8
	v_cmp_lt_i32_e64 s[8:9], s8, v92
	v_lshl_add_u64 v[104:105], v[102:103], 1, s[6:7]
	v_add3_u32 v103, 0, v3, v4
	v_writelane_b32 v246, s8, 40
	v_add_u32_e32 v3, -16, v100
	v_lshlrev_b32_e32 v108, 3, v12
	v_writelane_b32 v246, s9, 41
	v_mad_u64_u32 v[126:127], s[8:9], v3, s33, 0
	s_movk_i32 s8, 0xfeff
	v_ashrrev_i32_e32 v109, 31, v108
	v_mul_lo_u32 v3, v106, s10
	v_lshlrev_b32_e32 v4, 5, v12
	v_cmp_lt_i32_e64 s[8:9], s8, v92
	v_lshl_add_u64 v[110:111], v[108:109], 1, s[6:7]
	v_lshlrev_b32_e32 v114, 3, v16
	v_add3_u32 v109, 0, v3, v4
	v_writelane_b32 v246, s8, 42
	v_add_u32_e32 v3, -16, v106
	v_lshl_add_u64 v[130:131], s[4:5], 0, v[188:189]
	s_movk_i32 s4, 0xfcff
	v_ashrrev_i32_e32 v115, 31, v114
	v_writelane_b32 v246, s9, 43
	v_mad_u64_u32 v[128:129], s[8:9], v3, s33, 0
	v_mul_lo_u32 v3, v112, s10
	v_lshlrev_b32_e32 v4, 5, v16
	v_cmp_lt_i32_e64 s[4:5], s4, v92
	v_lshl_add_u64 v[116:117], v[114:115], 1, s[6:7]
	v_lshlrev_b32_e32 v120, 3, v18
	v_add3_u32 v115, 0, v3, v4
	v_writelane_b32 v246, s4, 44
	v_add_u32_e32 v3, -16, v112
	v_lshl_add_u64 v[134:135], s[0:1], 0, v[188:189]
	s_movk_i32 s0, 0xfaff
	v_ashrrev_i32_e32 v121, 31, v120
	v_writelane_b32 v246, s5, 45
	v_mad_u64_u32 v[132:133], s[4:5], v3, s33, 0
	v_mul_lo_u32 v3, v118, s10
	v_lshlrev_b32_e32 v4, 5, v18
	v_cmp_lt_i32_e64 s[0:1], s0, v92
	v_lshl_add_u64 v[122:123], v[120:121], 1, s[6:7]
	v_add3_u32 v121, 0, v3, v4
	v_writelane_b32 v246, s0, 46
	v_add_u32_e32 v3, -16, v118
	v_readlane_b32 s48, v247, 2
	v_writelane_b32 v246, s1, 47
	v_mad_u64_u32 v[136:137], s[0:1], v3, s33, 0
	v_readlane_b32 s0, v246, 17
	v_readlane_b32 s58, v247, 12
	v_readlane_b32 s59, v247, 13
	v_lshl_add_u32 v181, v1, 5, s0
	s_movk_i32 s0, 0x7c0
	v_and_b32_e32 v0, 0x1f8, v93
	v_readlane_b32 s60, v247, 14
	v_readlane_b32 s61, v247, 15
	v_cmp_gt_i32_e64 s[58:59], s0, v92
	s_movk_i32 s0, 0x5c0
	v_lshlrev_b32_e32 v2, 2, v0
	v_ashrrev_i32_e32 v138, 6, v92
	v_ashrrev_i32_e32 v140, 6, v6
	v_ashrrev_i32_e32 v142, 6, v10
	v_ashrrev_i32_e32 v144, 6, v14
	v_mov_b32_e32 v3, v189
	v_readlane_b32 s56, v247, 10
	v_readlane_b32 s57, v247, 11
	v_readlane_b32 s62, v247, 16
	v_readlane_b32 s63, v247, 17
	v_lshlrev_b32_e32 v188, 2, v1
	v_cmp_gt_i32_e64 s[60:61], s0, v92
	s_movk_i32 s0, 0x3c0
	v_lshl_add_u32 v168, v92, 2, 0
	v_add_u32_e32 v169, 0, v2
	v_lshlrev_b32_e32 v4, 11, v138
	v_lshl_add_u64 v[146:147], s[56:57], 0, v[2:3]
	v_lshl_add_u64 v[148:149], s[96:97], 0, v[2:3]
	v_lshlrev_b32_e32 v2, 11, v140
	v_lshlrev_b32_e32 v3, 11, v142
	v_lshlrev_b32_e32 v5, 11, v144
	v_lshl_add_u64 v[150:151], s[14:15], 0, v[188:189]
	v_lshlrev_b32_e32 v188, 1, v0
	v_cmp_gt_i32_e64 s[62:63], s0, v92
	s_movk_i32 s0, 0x1c0
	v_ashrrev_i32_e32 v95, 31, v94
	v_ashrrev_i32_e32 v101, 31, v100
	v_ashrrev_i32_e32 v107, 31, v106
	v_ashrrev_i32_e32 v113, 31, v112
	v_ashrrev_i32_e32 v119, 31, v118
	v_ashrrev_i32_e32 v139, 31, v138
	v_ashrrev_i32_e32 v141, 31, v140
	v_ashrrev_i32_e32 v143, 31, v142
	v_ashrrev_i32_e32 v145, 31, v144
	v_add_u32_e32 v178, 0x10200, v168
	v_add_u32_e32 v179, 0x10800, v168
	v_add_u32_e32 v180, 0x10e00, v168
	v_lshl_add_u64 v[152:153], s[14:15], 0, v[188:189]
	v_lshlrev_b32_e32 v154, 1, v0
	v_add_u32_e32 v182, v169, v4
	v_add_u32_e32 v183, v169, v2
	v_add_u32_e32 v202, v169, v3
	v_add_u32_e32 v203, v169, v5
	v_readlane_b32 s48, v244, 9
	v_cmp_gt_i32_e64 s[64:65], s0, v92
	s_mov_b64 s[4:5], 0
	v_readlane_b32 s49, v247, 3
	v_readlane_b32 s50, v247, 4
	v_readlane_b32 s51, v247, 5
	v_readlane_b32 s52, v247, 6
	v_readlane_b32 s53, v247, 7
	v_readlane_b32 s54, v247, 8
	v_readlane_b32 s55, v247, 9
	s_branch .LBB0_423

; #define GRID_BAR() xcd_barrier(xbar)
; __device__ __forceinline__ void mixer_mid(const Params& p, LAS unsigned char* lds, int G, int layer) {
;     ...
;     for (int ci = mx_r; ci < mx_tot; ci += mx_n) {
; __global__ void __launch_bounds__(512, 2) fwd_megakernel(Params p) {
;     ...
;             GRID_BAR();
; #pragma unroll 1
;             for (int rep = 0; rep < REP_MIX; ++rep)
;             mixer_mid(p, lds, G, layer);
;             GRID_BAR();
.LBB0_539:
	s_cmp_lg_u32 s101, 1
	s_cbranch_scc1 .Lpw_main_done
	s_mov_b32 s101, 0
	v_readlane_b32 s100, v244, 9
	s_add_u32 s100, s100, 32
	v_writelane_b32 v244, s100, 9
	s_movk_i32 s100, 0x84
	s_nop 0
	v_writelane_b32 v244, s100, 10
	v_readlane_b32 s100, v246, 29
	s_cmp_gt_u32 s100, 2
	s_cselect_b64 s[40:41], -1, 0
	s_waitcnt vmcnt(0) lgkmcnt(0)
	s_barrier
	s_branch .Lpw_bar2
